# prep weight copies: two items in flight per wave, contiguous per-wave item ranges rebalanced 7/2/11 between blocks that also run mod/bias items and the rest
# baseline (speedup 1.0000x reference)
.LBB0_583:
	v_readlane_b32 s0, v253, 12
	v_readlane_b32 s1, v253, 13
	s_andn2_b64 vcc, exec, s[0:1]
	s_waitcnt lgkmcnt(0)
	s_barrier
	s_cbranch_vccnz .LBB0_639
	v_lshlrev_b32_e32 v0, 3, v16
	v_bfe_u32 v4, v16, 3, 3
	v_and_b32_e32 v0, 56, v0
	v_and_b32_e32 v2, 31, v16
	v_bfe_u32 v3, v16, 5, 1
	v_mul_u32_u24_e32 v1, 0x84, v0
	v_lshlrev_b32_e32 v5, 2, v4
	v_readlane_b32 s0, v253, 30
	s_add_u32 s2, s2, 0x800000
	v_lshlrev_b32_e32 v9, 2, v2
	v_add3_u32 v5, s0, v1, v5
	v_mul_u32_u24_e32 v1, 0x84, v3
	s_addc_u32 s18, s11, 0
	v_or_b32_e32 v6, 8, v4
	v_or_b32_e32 v7, 16, v4
	v_or_b32_e32 v8, 24, v4
	v_add3_u32 v9, v1, v9, s0
	v_lshlrev_b32_e32 v160, 1, v0
	v_readlane_b32 s19, v254, 47
	v_readlane_b32 s12, v252, 23
	v_readlane_b32 s0, v252, 20
	s_nop 3
	s_cmp_lt_u32 s0, 96
	s_cbranch_scc1 .Lw3_lo
	s_cmp_lt_u32 s0, 100
	s_cbranch_scc1 .Lw3_mid
	s_sub_i32 s19, s19, 800
	s_mul_i32 s19, s19, 11
	s_add_i32 s19, s19, 5440
	s_add_i32 s0, s19, 11
	s_branch .Lw3_set
.Lw3_mid:
	s_sub_i32 s19, s19, 768
	s_lshl_b32 s19, s19, 1
	s_add_i32 s19, s19, 5376
	s_add_i32 s0, s19, 2
	s_branch .Lw3_set
.Lw3_lo:
	s_mul_i32 s19, s19, 7
	s_add_i32 s0, s19, 7
.Lw3_set:
	s_min_i32 s0, s0, 0x4908
	s_nop 0
	v_writelane_b32 v255, s0, 10
	s_mov_b32 s12, 1
	s_cmp_ge_i32 s19, s0
	s_cbranch_scc1 .LBB0_639

.LBB0_623:
	s_mov_b32 s20, s21
	s_mov_b64 s[4:5], s[12:13]
	s_mov_b32 s12, 1
	s_branch .LBB0_625

.LBB0_625:
	s_sext_i32_i16 s6, s22
	v_cvt_f32_i32_e32 v0, s6
	s_sext_i32_i16 s7, s20
	v_cvt_f32_i32_e32 v1, s7
	s_xor_b32 s6, s7, s6
	v_rcp_iflag_f32_e32 v10, v0
	s_ashr_i32 s6, s6, 30
	s_or_b32 s9, s6, 1
	v_mul_f32_e32 v10, v1, v10
	v_trunc_f32_e32 v10, v10
	v_fma_f32 v1, -v10, v0, v1
	v_cvt_i32_f32_e32 v10, v10
	v_cmp_ge_f32_e64 s[6:7], |v1|, |v0|
	s_and_b64 s[6:7], s[6:7], exec
	s_cselect_b32 s6, s9, 0
	v_readfirstlane_b32 s16, v10
	s_add_i32 s16, s16, s6
	s_mul_i32 s6, s16, s22
	s_sub_i32 s6, s20, s6
	s_sext_i32_i16 s6, s6
	s_lshl_b32 s9, s6, 5
	v_or_b32_e32 v0, s9, v2
	s_movk_i32 s6, 0xbff
	v_cmp_lt_i32_e32 vcc, s6, v0
	s_xor_b64 s[0:1], s[0:1], -1
	s_and_b64 s[0:1], s[0:1], vcc
	s_and_saveexec_b64 s[6:7], s[0:1]
	s_cbranch_execz .LBB0_635
	s_cmpk_gt_u32 s9, 0x10ff
	s_mov_b64 s[0:1], -1
	s_cbranch_scc0 .LBB0_632
	s_movk_i32 s0, 0x1107
	v_cmp_lt_u32_e32 vcc, s0, v0
	s_and_saveexec_b64 s[0:1], vcc
	s_xor_b64 s[12:13], exec, s[0:1]
	s_cmpk_lt_u32 s9, 0x1120
	s_cselect_b64 vcc, -1, 0
	s_cmpk_gt_u32 s9, 0x11ff
	v_add_u32_e32 v1, 0xffffff20, v0
	s_cselect_b64 s[0:1], -1, 0
	v_cndmask_b32_e64 v1, -1, v1, s[0:1]
	v_cndmask_b32_e32 v1, v1, v0, vcc
	s_andn2_saveexec_b64 s[0:1], s[12:13]
	v_add_u32_e32 v1, 0xfffffb00, v0
	s_or_b64 exec, exec, s[0:1]
	s_mov_b64 s[0:1], 0
	s_mov_b32 s12, 1

.LBB0_636:
	global_load_dword v78, v[0:1], off
	v_lshl_add_u64 v[0:1], v[0:1], 0, s[10:11]
	global_load_dword v79, v[0:1], off
	v_lshl_add_u64 v[0:1], v[0:1], 0, s[10:11]
	global_load_dword v80, v[0:1], off
	v_lshl_add_u64 v[0:1], v[0:1], 0, s[10:11]
	global_load_dword v81, v[0:1], off
	v_lshl_add_u64 v[0:1], v[0:1], 0, s[10:11]
	global_load_dword v82, v[0:1], off
	v_lshl_add_u64 v[0:1], v[0:1], 0, s[10:11]
	global_load_dword v83, v[0:1], off
	v_lshl_add_u64 v[0:1], v[0:1], 0, s[10:11]
	global_load_dword v84, v[0:1], off
	v_lshl_add_u64 v[0:1], v[0:1], 0, s[10:11]
	global_load_dword v85, v[0:1], off
	v_lshl_add_u64 v[0:1], v[0:1], 0, s[10:11]
	global_load_dword v86, v[0:1], off
	v_lshl_add_u64 v[0:1], v[0:1], 0, s[10:11]
	global_load_dword v87, v[0:1], off
	v_lshl_add_u64 v[0:1], v[0:1], 0, s[10:11]
	global_load_dword v88, v[0:1], off
	v_lshl_add_u64 v[0:1], v[0:1], 0, s[10:11]
	global_load_dword v89, v[0:1], off
	v_lshl_add_u64 v[0:1], v[0:1], 0, s[10:11]
	global_load_dword v90, v[0:1], off
	v_lshl_add_u64 v[0:1], v[0:1], 0, s[10:11]
	global_load_dword v91, v[0:1], off
	v_lshl_add_u64 v[0:1], v[0:1], 0, s[10:11]
	global_load_dword v92, v[0:1], off
	v_lshl_add_u64 v[0:1], v[0:1], 0, s[10:11]
	global_load_dword v93, v[0:1], off
	v_lshl_add_u64 v[0:1], v[0:1], 0, s[10:11]
	global_load_dword v94, v[0:1], off
	v_lshl_add_u64 v[0:1], v[0:1], 0, s[10:11]
	global_load_dword v95, v[0:1], off
	v_lshl_add_u64 v[0:1], v[0:1], 0, s[10:11]
	global_load_dword v96, v[0:1], off
	v_lshl_add_u64 v[0:1], v[0:1], 0, s[10:11]
	global_load_dword v97, v[0:1], off
	v_lshl_add_u64 v[0:1], v[0:1], 0, s[10:11]
	global_load_dword v98, v[0:1], off
	v_lshl_add_u64 v[0:1], v[0:1], 0, s[10:11]
	global_load_dword v99, v[0:1], off
	v_lshl_add_u64 v[0:1], v[0:1], 0, s[10:11]
	global_load_dword v100, v[0:1], off
	v_lshl_add_u64 v[0:1], v[0:1], 0, s[10:11]
	global_load_dword v101, v[0:1], off
	v_lshl_add_u64 v[0:1], v[0:1], 0, s[10:11]
	global_load_dword v102, v[0:1], off
	v_lshl_add_u64 v[0:1], v[0:1], 0, s[10:11]
	global_load_dword v103, v[0:1], off
	v_lshl_add_u64 v[0:1], v[0:1], 0, s[10:11]
	global_load_dword v104, v[0:1], off
	v_lshl_add_u64 v[0:1], v[0:1], 0, s[10:11]
	global_load_dword v105, v[0:1], off
	v_lshl_add_u64 v[0:1], v[0:1], 0, s[10:11]
	global_load_dword v106, v[0:1], off
	v_lshl_add_u64 v[0:1], v[0:1], 0, s[10:11]
	global_load_dword v107, v[0:1], off
	v_lshl_add_u64 v[0:1], v[0:1], 0, s[10:11]
	global_load_dword v108, v[0:1], off
	v_lshl_add_u64 v[0:1], v[0:1], 0, s[10:11]
	global_load_dword v109, v[0:1], off
	v_lshl_add_u64 v[0:1], v[0:1], 0, s[10:11]
	s_mov_b64 s[100:101], vcc
	s_ashr_i32 s1, s0, 31
	s_lshl_b64 s[0:1], s[0:1], 1
	s_add_u32 s0, s4, s0
	s_addc_u32 s1, s5, s1
	v_lshl_add_u64 v[150:151], s[0:1], 0, v[160:161]
	v_or_b32_e32 v14, s9, v4
	v_mul_hi_i32_i24_e32 v15, s8, v14
	v_mul_i32_i24_e32 v14, s8, v14
	v_lshl_add_u64 v[142:143], v[14:15], 1, v[150:151]
	v_or_b32_e32 v14, s9, v6
	v_mul_hi_i32_i24_e32 v15, s8, v14
	v_mul_i32_i24_e32 v14, s8, v14
	v_lshl_add_u64 v[144:145], v[14:15], 1, v[150:151]
	v_or_b32_e32 v14, s9, v7
	v_mul_hi_i32_i24_e32 v15, s8, v14
	v_mul_i32_i24_e32 v14, s8, v14
	v_lshl_add_u64 v[146:147], v[14:15], 1, v[150:151]
	v_or_b32_e32 v14, s9, v8
	v_mul_hi_i32_i24_e32 v15, s8, v14
	v_mul_i32_i24_e32 v14, s8, v14
	v_lshl_add_u64 v[148:149], v[14:15], 1, v[150:151]
	s_add_i32 s19, s19, s12
	v_readlane_b32 s0, v255, 10
	s_nop 3
	s_cmp_ge_i32 s19, s0
	s_cbranch_scc1 .Lw2_last
	s_mul_hi_i32 s0, s19, 0x3815e88f
	s_lshr_b32 s1, s0, 31
	s_ashr_i32 s0, s0, 11
	s_add_i32 s6, s0, s1
	s_mul_i32 s0, s6, 0x2484
	s_sub_i32 s20, s19, s0
	s_ashr_i32 s7, s6, 31
	s_mul_i32 s1, s6, 0x2500000
	s_mul_hi_i32 s0, s6, 0x2500000
	s_add_u32 s4, s2, s1
	s_addc_u32 s5, s18, s0
	s_cmpk_gt_i32 s20, 0xeff
	s_cselect_b64 s[0:1], -1, 0
	s_mov_b64 s[8:9], -1
	s_and_b64 vcc, exec, s[0:1]
	s_cbranch_vccnz .Lw2_587
	v_mov_b32_e32 v0, 48
	s_mul_i32 s9, s6, 0x1d20000
	v_add_u32_e32 v0, 0, v0
	v_add_u32_e32 v0, 0x20400, v0
	ds_read_b64 v[0:1], v0
	s_mul_hi_i32 s8, s6, 0x1d20000
	s_waitcnt lgkmcnt(0)
	v_readfirstlane_b32 s10, v0
	v_readfirstlane_b32 s11, v1
	s_add_u32 s10, s10, s9
	s_addc_u32 s11, s11, s8
	s_mov_b64 s[8:9], 0

.Lw2_635:
	s_or_b64 exec, exec, s[6:7]
	s_sext_i32_i16 s0, s16
	s_lshl_b32 s0, s0, 6
	v_or_b32_e32 v1, s0, v3
	v_cmp_lt_i32_e32 vcc, -1, v0
	v_mul_hi_i32_i24_e32 v11, s14, v1
	v_mul_i32_i24_e32 v10, s14, v1
	v_cndmask_b32_e32 v0, 0, v0, vcc
	v_lshl_add_u64 v[10:11], v[10:11], 2, s[10:11]
	v_ashrrev_i32_e32 v1, 31, v0
	s_mov_b32 s1, 0
	v_lshl_add_u64 v[0:1], v[0:1], 2, v[10:11]
	s_lshl_b64 s[6:7], s[14:15], 6
	s_lshl_b64 s[10:11], s[14:15], 3
	global_load_dword v110, v[0:1], off
	v_lshl_add_u64 v[0:1], v[0:1], 0, s[10:11]
	global_load_dword v111, v[0:1], off
	v_lshl_add_u64 v[0:1], v[0:1], 0, s[10:11]
	global_load_dword v112, v[0:1], off
	v_lshl_add_u64 v[0:1], v[0:1], 0, s[10:11]
	global_load_dword v113, v[0:1], off
	v_lshl_add_u64 v[0:1], v[0:1], 0, s[10:11]
	global_load_dword v114, v[0:1], off
	v_lshl_add_u64 v[0:1], v[0:1], 0, s[10:11]
	global_load_dword v115, v[0:1], off
	v_lshl_add_u64 v[0:1], v[0:1], 0, s[10:11]
	global_load_dword v116, v[0:1], off
	v_lshl_add_u64 v[0:1], v[0:1], 0, s[10:11]
	global_load_dword v117, v[0:1], off
	v_lshl_add_u64 v[0:1], v[0:1], 0, s[10:11]
	global_load_dword v118, v[0:1], off
	v_lshl_add_u64 v[0:1], v[0:1], 0, s[10:11]
	global_load_dword v119, v[0:1], off
	v_lshl_add_u64 v[0:1], v[0:1], 0, s[10:11]
	global_load_dword v120, v[0:1], off
	v_lshl_add_u64 v[0:1], v[0:1], 0, s[10:11]
	global_load_dword v121, v[0:1], off
	v_lshl_add_u64 v[0:1], v[0:1], 0, s[10:11]
	global_load_dword v122, v[0:1], off
	v_lshl_add_u64 v[0:1], v[0:1], 0, s[10:11]
	global_load_dword v123, v[0:1], off
	v_lshl_add_u64 v[0:1], v[0:1], 0, s[10:11]
	global_load_dword v124, v[0:1], off
	v_lshl_add_u64 v[0:1], v[0:1], 0, s[10:11]
	global_load_dword v125, v[0:1], off
	v_lshl_add_u64 v[0:1], v[0:1], 0, s[10:11]
	global_load_dword v126, v[0:1], off
	v_lshl_add_u64 v[0:1], v[0:1], 0, s[10:11]
	global_load_dword v127, v[0:1], off
	v_lshl_add_u64 v[0:1], v[0:1], 0, s[10:11]
	global_load_dword v128, v[0:1], off
	v_lshl_add_u64 v[0:1], v[0:1], 0, s[10:11]
	global_load_dword v129, v[0:1], off
	v_lshl_add_u64 v[0:1], v[0:1], 0, s[10:11]
	global_load_dword v130, v[0:1], off
	v_lshl_add_u64 v[0:1], v[0:1], 0, s[10:11]
	global_load_dword v131, v[0:1], off
	v_lshl_add_u64 v[0:1], v[0:1], 0, s[10:11]
	global_load_dword v132, v[0:1], off
	v_lshl_add_u64 v[0:1], v[0:1], 0, s[10:11]
	global_load_dword v133, v[0:1], off
	v_lshl_add_u64 v[0:1], v[0:1], 0, s[10:11]
	global_load_dword v134, v[0:1], off
	v_lshl_add_u64 v[0:1], v[0:1], 0, s[10:11]
	global_load_dword v135, v[0:1], off
	v_lshl_add_u64 v[0:1], v[0:1], 0, s[10:11]
	global_load_dword v136, v[0:1], off
	v_lshl_add_u64 v[0:1], v[0:1], 0, s[10:11]
	global_load_dword v137, v[0:1], off
	v_lshl_add_u64 v[0:1], v[0:1], 0, s[10:11]
	global_load_dword v138, v[0:1], off
	v_lshl_add_u64 v[0:1], v[0:1], 0, s[10:11]
	global_load_dword v139, v[0:1], off
	v_lshl_add_u64 v[0:1], v[0:1], 0, s[10:11]
	global_load_dword v140, v[0:1], off
	v_lshl_add_u64 v[0:1], v[0:1], 0, s[10:11]
	global_load_dword v141, v[0:1], off
	v_lshl_add_u64 v[0:1], v[0:1], 0, s[10:11]
	s_ashr_i32 s1, s0, 31
	s_lshl_b64 s[0:1], s[0:1], 1
	s_add_u32 s0, s4, s0
	s_addc_u32 s1, s5, s1
	v_lshl_add_u64 v[150:151], s[0:1], 0, v[160:161]
	v_or_b32_e32 v14, s9, v4
	v_mul_hi_i32_i24_e32 v15, s8, v14
	v_mul_i32_i24_e32 v14, s8, v14
	v_lshl_add_u64 v[152:153], v[14:15], 1, v[150:151]
	v_or_b32_e32 v14, s9, v6
	v_mul_hi_i32_i24_e32 v15, s8, v14
	v_mul_i32_i24_e32 v14, s8, v14
	v_lshl_add_u64 v[154:155], v[14:15], 1, v[150:151]
	v_or_b32_e32 v14, s9, v7
	v_mul_hi_i32_i24_e32 v15, s8, v14
	v_mul_i32_i24_e32 v14, s8, v14
	v_lshl_add_u64 v[156:157], v[14:15], 1, v[150:151]
	v_or_b32_e32 v14, s9, v8
	v_mul_hi_i32_i24_e32 v15, s8, v14
	v_mul_i32_i24_e32 v14, s8, v14
	v_lshl_add_u64 v[158:159], v[14:15], 1, v[150:151]
	s_waitcnt vmcnt(63)
	v_cndmask_b32_e64 v78, 0, v78, s[100:101]
	ds_write_b32 v9, v78
	s_waitcnt vmcnt(62)
	v_cndmask_b32_e64 v79, 0, v79, s[100:101]
	ds_write_b32 v9, v79 offset:264
	s_waitcnt vmcnt(61)
	v_cndmask_b32_e64 v80, 0, v80, s[100:101]
	ds_write_b32 v9, v80 offset:528
	s_waitcnt vmcnt(60)
	v_cndmask_b32_e64 v81, 0, v81, s[100:101]
	ds_write_b32 v9, v81 offset:792
	s_waitcnt vmcnt(59)
	v_cndmask_b32_e64 v82, 0, v82, s[100:101]
	ds_write_b32 v9, v82 offset:1056
	s_waitcnt vmcnt(58)
	v_cndmask_b32_e64 v83, 0, v83, s[100:101]
	ds_write_b32 v9, v83 offset:1320
	s_waitcnt vmcnt(57)
	v_cndmask_b32_e64 v84, 0, v84, s[100:101]
	ds_write_b32 v9, v84 offset:1584
	s_waitcnt vmcnt(56)
	v_cndmask_b32_e64 v85, 0, v85, s[100:101]
	ds_write_b32 v9, v85 offset:1848
	s_waitcnt vmcnt(55)
	v_cndmask_b32_e64 v86, 0, v86, s[100:101]
	ds_write_b32 v9, v86 offset:2112
	s_waitcnt vmcnt(54)
	v_cndmask_b32_e64 v87, 0, v87, s[100:101]
	ds_write_b32 v9, v87 offset:2376
	s_waitcnt vmcnt(53)
	v_cndmask_b32_e64 v88, 0, v88, s[100:101]
	ds_write_b32 v9, v88 offset:2640
	s_waitcnt vmcnt(52)
	v_cndmask_b32_e64 v89, 0, v89, s[100:101]
	ds_write_b32 v9, v89 offset:2904
	s_waitcnt vmcnt(51)
	v_cndmask_b32_e64 v90, 0, v90, s[100:101]
	ds_write_b32 v9, v90 offset:3168
	s_waitcnt vmcnt(50)
	v_cndmask_b32_e64 v91, 0, v91, s[100:101]
	ds_write_b32 v9, v91 offset:3432
	s_waitcnt vmcnt(49)
	v_cndmask_b32_e64 v92, 0, v92, s[100:101]
	ds_write_b32 v9, v92 offset:3696
	s_waitcnt vmcnt(48)
	v_cndmask_b32_e64 v93, 0, v93, s[100:101]
	ds_write_b32 v9, v93 offset:3960
	s_waitcnt vmcnt(47)
	v_cndmask_b32_e64 v94, 0, v94, s[100:101]
	ds_write_b32 v9, v94 offset:4224
	s_waitcnt vmcnt(46)
	v_cndmask_b32_e64 v95, 0, v95, s[100:101]
	ds_write_b32 v9, v95 offset:4488
	s_waitcnt vmcnt(45)
	v_cndmask_b32_e64 v96, 0, v96, s[100:101]
	ds_write_b32 v9, v96 offset:4752
	s_waitcnt vmcnt(44)
	v_cndmask_b32_e64 v97, 0, v97, s[100:101]
	ds_write_b32 v9, v97 offset:5016
	s_waitcnt vmcnt(43)
	v_cndmask_b32_e64 v98, 0, v98, s[100:101]
	ds_write_b32 v9, v98 offset:5280
	s_waitcnt vmcnt(42)
	v_cndmask_b32_e64 v99, 0, v99, s[100:101]
	ds_write_b32 v9, v99 offset:5544
	s_waitcnt vmcnt(41)
	v_cndmask_b32_e64 v100, 0, v100, s[100:101]
	ds_write_b32 v9, v100 offset:5808
	s_waitcnt vmcnt(40)
	v_cndmask_b32_e64 v101, 0, v101, s[100:101]
	ds_write_b32 v9, v101 offset:6072
	s_waitcnt vmcnt(39)
	v_cndmask_b32_e64 v102, 0, v102, s[100:101]
	ds_write_b32 v9, v102 offset:6336
	s_waitcnt vmcnt(38)
	v_cndmask_b32_e64 v103, 0, v103, s[100:101]
	ds_write_b32 v9, v103 offset:6600
	s_waitcnt vmcnt(37)
	v_cndmask_b32_e64 v104, 0, v104, s[100:101]
	ds_write_b32 v9, v104 offset:6864
	s_waitcnt vmcnt(36)
	v_cndmask_b32_e64 v105, 0, v105, s[100:101]
	ds_write_b32 v9, v105 offset:7128
	s_waitcnt vmcnt(35)
	v_cndmask_b32_e64 v106, 0, v106, s[100:101]
	ds_write_b32 v9, v106 offset:7392
	s_waitcnt vmcnt(34)
	v_cndmask_b32_e64 v107, 0, v107, s[100:101]
	ds_write_b32 v9, v107 offset:7656
	s_waitcnt vmcnt(33)
	v_cndmask_b32_e64 v108, 0, v108, s[100:101]
	ds_write_b32 v9, v108 offset:7920
	s_waitcnt vmcnt(32)
	v_cndmask_b32_e64 v109, 0, v109, s[100:101]
	ds_write_b32 v9, v109 offset:8184
	ds_read_b32 v10, v5
	ds_read_b32 v11, v5 offset:132
	ds_read_b32 v12, v5 offset:264
	ds_read_b32 v13, v5 offset:396
	ds_read_b32 v14, v5 offset:528
	ds_read_b32 v15, v5 offset:660
	ds_read_b32 v16, v5 offset:792
	ds_read_b32 v17, v5 offset:924
	s_waitcnt lgkmcnt(0)
	v_cvt_pk_bf16_f32 v10, v10, v11
	v_cvt_pk_bf16_f32 v11, v12, v13
	v_cvt_pk_bf16_f32 v12, v14, v15
	v_cvt_pk_bf16_f32 v13, v16, v17
	global_store_dwordx4 v[142:143], v[10:13], off
	ds_read_b32 v10, v5 offset:32
	ds_read_b32 v11, v5 offset:164
	ds_read_b32 v12, v5 offset:296
	ds_read_b32 v13, v5 offset:428
	ds_read_b32 v14, v5 offset:560
	ds_read_b32 v15, v5 offset:692
	ds_read_b32 v16, v5 offset:824
	ds_read_b32 v17, v5 offset:956
	s_waitcnt lgkmcnt(0)
	v_cvt_pk_bf16_f32 v10, v10, v11
	v_cvt_pk_bf16_f32 v11, v12, v13
	v_cvt_pk_bf16_f32 v12, v14, v15
	v_cvt_pk_bf16_f32 v13, v16, v17
	global_store_dwordx4 v[144:145], v[10:13], off
	ds_read_b32 v10, v5 offset:64
	ds_read_b32 v11, v5 offset:196
	ds_read_b32 v12, v5 offset:328
	ds_read_b32 v13, v5 offset:460
	ds_read_b32 v14, v5 offset:592
	ds_read_b32 v15, v5 offset:724
	ds_read_b32 v16, v5 offset:856
	ds_read_b32 v17, v5 offset:988
	s_waitcnt lgkmcnt(0)
	v_cvt_pk_bf16_f32 v10, v10, v11
	v_cvt_pk_bf16_f32 v11, v12, v13
	v_cvt_pk_bf16_f32 v12, v14, v15
	v_cvt_pk_bf16_f32 v13, v16, v17
	global_store_dwordx4 v[146:147], v[10:13], off
	ds_read_b32 v10, v5 offset:96
	ds_read_b32 v11, v5 offset:228
	ds_read_b32 v12, v5 offset:360
	ds_read_b32 v13, v5 offset:492
	ds_read_b32 v14, v5 offset:624
	ds_read_b32 v15, v5 offset:756
	ds_read_b32 v16, v5 offset:888
	ds_read_b32 v17, v5 offset:1020
	s_waitcnt lgkmcnt(0)
	v_cvt_pk_bf16_f32 v10, v10, v11
	v_cvt_pk_bf16_f32 v11, v12, v13
	v_cvt_pk_bf16_f32 v12, v14, v15
	v_cvt_pk_bf16_f32 v13, v16, v17
	global_store_dwordx4 v[148:149], v[10:13], off
	s_waitcnt vmcnt(35)
	v_cndmask_b32_e32 v110, 0, v110, vcc
	ds_write_b32 v9, v110
	s_waitcnt vmcnt(34)
	v_cndmask_b32_e32 v111, 0, v111, vcc
	ds_write_b32 v9, v111 offset:264
	s_waitcnt vmcnt(33)
	v_cndmask_b32_e32 v112, 0, v112, vcc
	ds_write_b32 v9, v112 offset:528
	s_waitcnt vmcnt(32)
	v_cndmask_b32_e32 v113, 0, v113, vcc
	ds_write_b32 v9, v113 offset:792
	s_waitcnt vmcnt(31)
	v_cndmask_b32_e32 v114, 0, v114, vcc
	ds_write_b32 v9, v114 offset:1056
	s_waitcnt vmcnt(30)
	v_cndmask_b32_e32 v115, 0, v115, vcc
	ds_write_b32 v9, v115 offset:1320
	s_waitcnt vmcnt(29)
	v_cndmask_b32_e32 v116, 0, v116, vcc
	ds_write_b32 v9, v116 offset:1584
	s_waitcnt vmcnt(28)
	v_cndmask_b32_e32 v117, 0, v117, vcc
	ds_write_b32 v9, v117 offset:1848
	s_waitcnt vmcnt(27)
	v_cndmask_b32_e32 v118, 0, v118, vcc
	ds_write_b32 v9, v118 offset:2112
	s_waitcnt vmcnt(26)
	v_cndmask_b32_e32 v119, 0, v119, vcc
	ds_write_b32 v9, v119 offset:2376
	s_waitcnt vmcnt(25)
	v_cndmask_b32_e32 v120, 0, v120, vcc
	ds_write_b32 v9, v120 offset:2640
	s_waitcnt vmcnt(24)
	v_cndmask_b32_e32 v121, 0, v121, vcc
	ds_write_b32 v9, v121 offset:2904
	s_waitcnt vmcnt(23)
	v_cndmask_b32_e32 v122, 0, v122, vcc
	ds_write_b32 v9, v122 offset:3168
	s_waitcnt vmcnt(22)
	v_cndmask_b32_e32 v123, 0, v123, vcc
	ds_write_b32 v9, v123 offset:3432
	s_waitcnt vmcnt(21)
	v_cndmask_b32_e32 v124, 0, v124, vcc
	ds_write_b32 v9, v124 offset:3696
	s_waitcnt vmcnt(20)
	v_cndmask_b32_e32 v125, 0, v125, vcc
	ds_write_b32 v9, v125 offset:3960
	s_waitcnt vmcnt(19)
	v_cndmask_b32_e32 v126, 0, v126, vcc
	ds_write_b32 v9, v126 offset:4224
	s_waitcnt vmcnt(18)
	v_cndmask_b32_e32 v127, 0, v127, vcc
	ds_write_b32 v9, v127 offset:4488
	s_waitcnt vmcnt(17)
	v_cndmask_b32_e32 v128, 0, v128, vcc
	ds_write_b32 v9, v128 offset:4752
	s_waitcnt vmcnt(16)
	v_cndmask_b32_e32 v129, 0, v129, vcc
	ds_write_b32 v9, v129 offset:5016
	s_waitcnt vmcnt(15)
	v_cndmask_b32_e32 v130, 0, v130, vcc
	ds_write_b32 v9, v130 offset:5280
	s_waitcnt vmcnt(14)
	v_cndmask_b32_e32 v131, 0, v131, vcc
	ds_write_b32 v9, v131 offset:5544
	s_waitcnt vmcnt(13)
	v_cndmask_b32_e32 v132, 0, v132, vcc
	ds_write_b32 v9, v132 offset:5808
	s_waitcnt vmcnt(12)
	v_cndmask_b32_e32 v133, 0, v133, vcc
	ds_write_b32 v9, v133 offset:6072
	s_waitcnt vmcnt(11)
	v_cndmask_b32_e32 v134, 0, v134, vcc
	ds_write_b32 v9, v134 offset:6336
	s_waitcnt vmcnt(10)
	v_cndmask_b32_e32 v135, 0, v135, vcc
	ds_write_b32 v9, v135 offset:6600
	s_waitcnt vmcnt(9)
	v_cndmask_b32_e32 v136, 0, v136, vcc
	ds_write_b32 v9, v136 offset:6864
	s_waitcnt vmcnt(8)
	v_cndmask_b32_e32 v137, 0, v137, vcc
	ds_write_b32 v9, v137 offset:7128
	s_waitcnt vmcnt(7)
	v_cndmask_b32_e32 v138, 0, v138, vcc
	ds_write_b32 v9, v138 offset:7392
	s_waitcnt vmcnt(6)
	v_cndmask_b32_e32 v139, 0, v139, vcc
	ds_write_b32 v9, v139 offset:7656
	s_waitcnt vmcnt(5)
	v_cndmask_b32_e32 v140, 0, v140, vcc
	ds_write_b32 v9, v140 offset:7920
	s_waitcnt vmcnt(4)
	v_cndmask_b32_e32 v141, 0, v141, vcc
	ds_write_b32 v9, v141 offset:8184
	ds_read_b32 v10, v5
	ds_read_b32 v11, v5 offset:132
	ds_read_b32 v12, v5 offset:264
	ds_read_b32 v13, v5 offset:396
	ds_read_b32 v14, v5 offset:528
	ds_read_b32 v15, v5 offset:660
	ds_read_b32 v16, v5 offset:792
	ds_read_b32 v17, v5 offset:924
	s_waitcnt lgkmcnt(0)
	v_cvt_pk_bf16_f32 v10, v10, v11
	v_cvt_pk_bf16_f32 v11, v12, v13
	v_cvt_pk_bf16_f32 v12, v14, v15
	v_cvt_pk_bf16_f32 v13, v16, v17
	global_store_dwordx4 v[152:153], v[10:13], off
	ds_read_b32 v10, v5 offset:32
	ds_read_b32 v11, v5 offset:164
	ds_read_b32 v12, v5 offset:296
	ds_read_b32 v13, v5 offset:428
	ds_read_b32 v14, v5 offset:560
	ds_read_b32 v15, v5 offset:692
	ds_read_b32 v16, v5 offset:824
	ds_read_b32 v17, v5 offset:956
	s_waitcnt lgkmcnt(0)
	v_cvt_pk_bf16_f32 v10, v10, v11
	v_cvt_pk_bf16_f32 v11, v12, v13
	v_cvt_pk_bf16_f32 v12, v14, v15
	v_cvt_pk_bf16_f32 v13, v16, v17
	global_store_dwordx4 v[154:155], v[10:13], off
	ds_read_b32 v10, v5 offset:64
	ds_read_b32 v11, v5 offset:196
	ds_read_b32 v12, v5 offset:328
	ds_read_b32 v13, v5 offset:460
	ds_read_b32 v14, v5 offset:592
	ds_read_b32 v15, v5 offset:724
	ds_read_b32 v16, v5 offset:856
	ds_read_b32 v17, v5 offset:988
	s_waitcnt lgkmcnt(0)
	v_cvt_pk_bf16_f32 v10, v10, v11
	v_cvt_pk_bf16_f32 v11, v12, v13
	v_cvt_pk_bf16_f32 v12, v14, v15
	v_cvt_pk_bf16_f32 v13, v16, v17
	global_store_dwordx4 v[156:157], v[10:13], off
	ds_read_b32 v10, v5 offset:96
	ds_read_b32 v11, v5 offset:228
	ds_read_b32 v12, v5 offset:360
	ds_read_b32 v13, v5 offset:492
	ds_read_b32 v14, v5 offset:624
	ds_read_b32 v15, v5 offset:756
	ds_read_b32 v16, v5 offset:888
	ds_read_b32 v17, v5 offset:1020
	s_waitcnt lgkmcnt(0)
	v_cvt_pk_bf16_f32 v10, v10, v11
	v_cvt_pk_bf16_f32 v11, v12, v13
	v_cvt_pk_bf16_f32 v12, v14, v15
	v_cvt_pk_bf16_f32 v13, v16, v17
	global_store_dwordx4 v[158:159], v[10:13], off
	s_add_i32 s19, s19, s12
	v_readlane_b32 s0, v255, 10
	s_nop 3
	s_cmp_ge_i32 s19, s0
	s_cbranch_scc0 .LBB0_585
	s_branch .LBB0_639
.Lw2_last:
	s_waitcnt vmcnt(0)
	s_waitcnt vmcnt(63)
	v_cndmask_b32_e64 v78, 0, v78, s[100:101]
	ds_write_b32 v9, v78
	s_waitcnt vmcnt(62)
	v_cndmask_b32_e64 v79, 0, v79, s[100:101]
	ds_write_b32 v9, v79 offset:264
	s_waitcnt vmcnt(61)
	v_cndmask_b32_e64 v80, 0, v80, s[100:101]
	ds_write_b32 v9, v80 offset:528
	s_waitcnt vmcnt(60)
	v_cndmask_b32_e64 v81, 0, v81, s[100:101]
	ds_write_b32 v9, v81 offset:792
	s_waitcnt vmcnt(59)
	v_cndmask_b32_e64 v82, 0, v82, s[100:101]
	ds_write_b32 v9, v82 offset:1056
	s_waitcnt vmcnt(58)
	v_cndmask_b32_e64 v83, 0, v83, s[100:101]
	ds_write_b32 v9, v83 offset:1320
	s_waitcnt vmcnt(57)
	v_cndmask_b32_e64 v84, 0, v84, s[100:101]
	ds_write_b32 v9, v84 offset:1584
	s_waitcnt vmcnt(56)
	v_cndmask_b32_e64 v85, 0, v85, s[100:101]
	ds_write_b32 v9, v85 offset:1848
	s_waitcnt vmcnt(55)
	v_cndmask_b32_e64 v86, 0, v86, s[100:101]
	ds_write_b32 v9, v86 offset:2112
	s_waitcnt vmcnt(54)
	v_cndmask_b32_e64 v87, 0, v87, s[100:101]
	ds_write_b32 v9, v87 offset:2376
	s_waitcnt vmcnt(53)
	v_cndmask_b32_e64 v88, 0, v88, s[100:101]
	ds_write_b32 v9, v88 offset:2640
	s_waitcnt vmcnt(52)
	v_cndmask_b32_e64 v89, 0, v89, s[100:101]
	ds_write_b32 v9, v89 offset:2904
	s_waitcnt vmcnt(51)
	v_cndmask_b32_e64 v90, 0, v90, s[100:101]
	ds_write_b32 v9, v90 offset:3168
	s_waitcnt vmcnt(50)
	v_cndmask_b32_e64 v91, 0, v91, s[100:101]
	ds_write_b32 v9, v91 offset:3432
	s_waitcnt vmcnt(49)
	v_cndmask_b32_e64 v92, 0, v92, s[100:101]
	ds_write_b32 v9, v92 offset:3696
	s_waitcnt vmcnt(48)
	v_cndmask_b32_e64 v93, 0, v93, s[100:101]
	ds_write_b32 v9, v93 offset:3960
	s_waitcnt vmcnt(47)
	v_cndmask_b32_e64 v94, 0, v94, s[100:101]
	ds_write_b32 v9, v94 offset:4224
	s_waitcnt vmcnt(46)
	v_cndmask_b32_e64 v95, 0, v95, s[100:101]
	ds_write_b32 v9, v95 offset:4488
	s_waitcnt vmcnt(45)
	v_cndmask_b32_e64 v96, 0, v96, s[100:101]
	ds_write_b32 v9, v96 offset:4752
	s_waitcnt vmcnt(44)
	v_cndmask_b32_e64 v97, 0, v97, s[100:101]
	ds_write_b32 v9, v97 offset:5016
	s_waitcnt vmcnt(43)
	v_cndmask_b32_e64 v98, 0, v98, s[100:101]
	ds_write_b32 v9, v98 offset:5280
	s_waitcnt vmcnt(42)
	v_cndmask_b32_e64 v99, 0, v99, s[100:101]
	ds_write_b32 v9, v99 offset:5544
	s_waitcnt vmcnt(41)
	v_cndmask_b32_e64 v100, 0, v100, s[100:101]
	ds_write_b32 v9, v100 offset:5808
	s_waitcnt vmcnt(40)
	v_cndmask_b32_e64 v101, 0, v101, s[100:101]
	ds_write_b32 v9, v101 offset:6072
	s_waitcnt vmcnt(39)
	v_cndmask_b32_e64 v102, 0, v102, s[100:101]
	ds_write_b32 v9, v102 offset:6336
	s_waitcnt vmcnt(38)
	v_cndmask_b32_e64 v103, 0, v103, s[100:101]
	ds_write_b32 v9, v103 offset:6600
	s_waitcnt vmcnt(37)
	v_cndmask_b32_e64 v104, 0, v104, s[100:101]
	ds_write_b32 v9, v104 offset:6864
	s_waitcnt vmcnt(36)
	v_cndmask_b32_e64 v105, 0, v105, s[100:101]
	ds_write_b32 v9, v105 offset:7128
	s_waitcnt vmcnt(35)
	v_cndmask_b32_e64 v106, 0, v106, s[100:101]
	ds_write_b32 v9, v106 offset:7392
	s_waitcnt vmcnt(34)
	v_cndmask_b32_e64 v107, 0, v107, s[100:101]
	ds_write_b32 v9, v107 offset:7656
	s_waitcnt vmcnt(33)
	v_cndmask_b32_e64 v108, 0, v108, s[100:101]
	ds_write_b32 v9, v108 offset:7920
	s_waitcnt vmcnt(32)
	v_cndmask_b32_e64 v109, 0, v109, s[100:101]
	ds_write_b32 v9, v109 offset:8184
	ds_read_b32 v10, v5
	ds_read_b32 v11, v5 offset:132
	ds_read_b32 v12, v5 offset:264
	ds_read_b32 v13, v5 offset:396
	ds_read_b32 v14, v5 offset:528
	ds_read_b32 v15, v5 offset:660
	ds_read_b32 v16, v5 offset:792
	ds_read_b32 v17, v5 offset:924
	s_waitcnt lgkmcnt(0)
	v_cvt_pk_bf16_f32 v10, v10, v11
	v_cvt_pk_bf16_f32 v11, v12, v13
	v_cvt_pk_bf16_f32 v12, v14, v15
	v_cvt_pk_bf16_f32 v13, v16, v17
	global_store_dwordx4 v[142:143], v[10:13], off
	ds_read_b32 v10, v5 offset:32
	ds_read_b32 v11, v5 offset:164
	ds_read_b32 v12, v5 offset:296
	ds_read_b32 v13, v5 offset:428
	ds_read_b32 v14, v5 offset:560
	ds_read_b32 v15, v5 offset:692
	ds_read_b32 v16, v5 offset:824
	ds_read_b32 v17, v5 offset:956
	s_waitcnt lgkmcnt(0)
	v_cvt_pk_bf16_f32 v10, v10, v11
	v_cvt_pk_bf16_f32 v11, v12, v13
	v_cvt_pk_bf16_f32 v12, v14, v15
	v_cvt_pk_bf16_f32 v13, v16, v17
	global_store_dwordx4 v[144:145], v[10:13], off
	ds_read_b32 v10, v5 offset:64
	ds_read_b32 v11, v5 offset:196
	ds_read_b32 v12, v5 offset:328
	ds_read_b32 v13, v5 offset:460
	ds_read_b32 v14, v5 offset:592
	ds_read_b32 v15, v5 offset:724
	ds_read_b32 v16, v5 offset:856
	ds_read_b32 v17, v5 offset:988
	s_waitcnt lgkmcnt(0)
	v_cvt_pk_bf16_f32 v10, v10, v11
	v_cvt_pk_bf16_f32 v11, v12, v13
	v_cvt_pk_bf16_f32 v12, v14, v15
	v_cvt_pk_bf16_f32 v13, v16, v17
	global_store_dwordx4 v[146:147], v[10:13], off
	ds_read_b32 v10, v5 offset:96
	ds_read_b32 v11, v5 offset:228
	ds_read_b32 v12, v5 offset:360
	ds_read_b32 v13, v5 offset:492
	ds_read_b32 v14, v5 offset:624
	ds_read_b32 v15, v5 offset:756
	ds_read_b32 v16, v5 offset:888
	ds_read_b32 v17, v5 offset:1020
	s_waitcnt lgkmcnt(0)
	v_cvt_pk_bf16_f32 v10, v10, v11
	v_cvt_pk_bf16_f32 v11, v12, v13
	v_cvt_pk_bf16_f32 v12, v14, v15
	v_cvt_pk_bf16_f32 v13, v16, v17
	global_store_dwordx4 v[148:149], v[10:13], off
	s_branch .LBB0_639
.LBB0_638:
	s_mov_b64 s[14:15], 64
	s_mov_b32 s22, 2
	s_cbranch_execz .LBB0_610
	s_branch .LBB0_611
.Lw2_638:
	s_mov_b64 s[14:15], 64
	s_mov_b32 s22, 2
	s_cbranch_execz .Lw2_610
	s_branch .Lw2_611
